# P2 epilogue sample rows: all eight carried-state loads hoisted, counted waits; one store-drain wait removed
# baseline (speedup 1.0000x reference)
; __device__ __forceinline__ unsigned cvt_pk_bf16(float lo, float hi) { unsigned r; asm volatile("v_cvt_pk_bf16_f32 %0, %1, %2" : "=v"(r) : "v"(lo), "v"(hi)); return r; }
;     __device__ __forceinline__ void operator()(const f32x4 (&acc)[2][2][4][2], const Unit& u, int wr, int wc, int fr, int fq) const {
;     ...
;                     if (m > 0 || fr >= 2) { u32x2 a; a.x = cvt_pk_bf16(ua[0], ua[1]); a.y = cvt_pk_bf16(ua[2], ua[3]); *(u32x2*)(rowp + C_UA) = a; }
;                     { u32x2 g; g.x = cvt_pk_bf16(ma[0], ma[1]); g.y = cvt_pk_bf16(ma[2], ma[3]); *(u32x2*)(rowp + C_MA) = g; }
;                     if (m == 0 && fr < 2) { const int blk = r >> 6; u32x2 a; a.x = cvt_pk_bf16(gb[0], gb[1]); a.y = cvt_pk_bf16(gb[2], gb[3]); *(u32x2*)(EFA + ((size_t)(blk * 2 + fr) * 2) * D + xch) = a;
;                         u32x2 q; q.x = cvt_pk_bf16(z[0][0], z[0][1]); q.y = cvt_pk_bf16(z[0][2], z[0][3]); *(u32x2*)(EFA + ((size_t)(blk * 2 + fr) * 2 + 1) * D + xch) = q; }
.LBB0_167:
	s_or_b64 exec, exec, s[14:15]
	s_ashr_i32 s55, s55, 5
	v_pk_add_f32 v[154:155], v[114:115], v[130:131]
	v_pk_add_f32 v[152:153], v[116:117], v[132:133]
	v_cvt_pk_bf16_f32 v154, v154, v155
	s_nop 0
	v_cvt_pk_bf16_f32 v155, v152, v153
	global_store_dwordx2 v[150:151], v[154:155], off offset:2048
	s_and_saveexec_b64 s[12:13], s[6:7]
	s_cbranch_execz .LBB0_169
	v_or_b32_e32 v150, s55, v184
	v_ashrrev_i32_e32 v151, 31, v150
	v_lshlrev_b64 v[150:151], 12, v[150:151]
	v_lshl_add_u64 v[150:151], s[68:69], 0, v[150:151]
	v_cvt_pk_bf16_f32 v152, v126, v127
	v_cvt_pk_bf16_f32 v153, v128, v129
	v_lshl_add_u64 v[150:151], v[176:177], 1, v[150:151]
	global_store_dwordx2 v[150:151], v[152:153], off
	v_cvt_pk_bf16_f32 v152, v146, v147
	v_cvt_pk_bf16_f32 v153, v148, v149
	global_store_dwordx2 v[150:151], v[152:153], off offset:2048

; __device__ __forceinline__ unsigned cvt_pk_bf16(float lo, float hi) { unsigned r; asm volatile("v_cvt_pk_bf16_f32 %0, %1, %2" : "=v"(r) : "v"(lo), "v"(hi)); return r; }
;     __device__ __forceinline__ void operator()(const f32x4 (&acc)[2][2][4][2], const Unit& u, int wr, int wc, int fr, int fq) const {
;     ...
;             if (u.pm == 64 && ai == 1) {
; #pragma unroll
;                 for (int m = 0; m < 4; ++m) { const int r = rbase + HALF + 16 * m, sb = r - MP;
;                     const f32x4 z2 = *(const f32x4*)(st + (size_t)(sb * 2) * D + xch), z1 = *(const f32x4*)(st + (size_t)(sb * 2 + 1) * D + xch);
;                     const f32x4 ua = acc[1][0][m][0] * (w0 * z2 + w1 * z1 + w2 * z[m]), ma = acc[1][1][m][1] + bm;
;                     bf16_t* rowp = O + (size_t)r * DP + xch;
;                     u32x2 a; a.x = cvt_pk_bf16(ua[0], ua[1]); a.y = cvt_pk_bf16(ua[2], ua[3]); *(u32x2*)(rowp + C_UA) = a;
;                     u32x2 g; g.x = cvt_pk_bf16(ma[0], ma[1]); g.y = cvt_pk_bf16(ma[2], ma[3]); *(u32x2*)(rowp + C_MA) = g;
;                     *(f32x4*)(outs + (size_t)(sb * 2) * D + xch) = z1; *(f32x4*)(outs + (size_t)(sb * 2 + 1) * D + xch) = z[m]; }
.LBB0_198:
	v_lshlrev_b32_e32 v0, 1, v182
	v_add_u32_e32 v180, 0xffff7f00, v0
	v_ashrrev_i32_e32 v181, 31, v180
	v_lshlrev_b64 v[200:201], 12, v[180:181]
	v_lshl_add_u64 v[180:181], s[74:75], 0, v[200:201]
	v_lshl_add_u64 v[180:181], v[180:181], 0, v[178:179]
	global_load_dwordx4 v[66:69], v[180:181], off
	s_mov_b64 s[98:99], 0x1000
	v_lshl_add_u64 v[238:239], v[180:181], 0, s[98:99]
	global_load_dwordx4 v[70:73], v[238:239], off
	s_mov_b64 s[98:99], 0x20000
	v_lshl_add_u64 v[238:239], v[180:181], 0, s[98:99]
	global_load_dwordx4 v[74:77], v[238:239], off
	s_mov_b64 s[98:99], 0x21000
	v_lshl_add_u64 v[238:239], v[180:181], 0, s[98:99]
	global_load_dwordx4 v[78:81], v[238:239], off
	s_mov_b64 s[98:99], 0x40000
	v_lshl_add_u64 v[238:239], v[180:181], 0, s[98:99]
	global_load_dwordx4 v[82:85], v[238:239], off
	s_mov_b64 s[98:99], 0x41000
	v_lshl_add_u64 v[238:239], v[180:181], 0, s[98:99]
	global_load_dwordx4 v[86:89], v[238:239], off
	s_mov_b64 s[98:99], 0x60000
	v_lshl_add_u64 v[238:239], v[180:181], 0, s[98:99]
	global_load_dwordx4 v[90:93], v[238:239], off
	s_mov_b64 s[98:99], 0x61000
	v_lshl_add_u64 v[238:239], v[180:181], 0, s[98:99]
	global_load_dwordx4 v[94:97], v[238:239], off
	v_add_u32_e32 v180, 0xffff7f01, v0
	v_ashrrev_i32_e32 v181, 31, v180
	v_lshlrev_b64 v[202:203], 12, v[180:181]
	v_lshl_add_u64 v[180:181], s[74:75], 0, v[202:203]
	v_lshl_add_u64 v[180:181], v[180:181], 0, v[178:179]
	v_pk_add_f32 v[226:227], v[46:47], v[130:131]
	v_add_u32_e32 v0, 0x90, v190
	v_lshlrev_b32_e32 v191, 1, v0
	s_or_b64 s[14:15], s[14:15], exec
	s_waitcnt vmcnt(6)
	v_mov_b64_e32 v[192:193], v[66:67]
	v_mov_b64_e32 v[194:195], v[68:69]
	v_mov_b64_e32 v[196:197], v[70:71]
	v_mov_b64_e32 v[198:199], v[72:73]
	v_pk_mul_f32 v[180:181], v[144:145], v[198:199]
	v_pk_mul_f32 v[224:225], v[142:143], v[196:197]
	v_pk_fma_f32 v[180:181], v[136:137], v[194:195], v[180:181]
	v_pk_fma_f32 v[192:193], v[134:135], v[192:193], v[224:225]
	v_pk_fma_f32 v[180:181], v[160:161], v[140:141], v[180:181]
	v_pk_fma_f32 v[192:193], v[158:159], v[138:139], v[192:193]
	v_pk_mul_f32 v[194:195], v[64:65], v[180:181]
	v_mov_b64_e32 v[180:181], s[64:65]
	v_pk_mul_f32 v[192:193], v[62:63], v[192:193]
	v_mad_i64_i32 v[228:229], s[12:13], v182, s33, v[180:181]
	v_lshlrev_b64 v[182:183], 1, v[176:177]
	v_lshl_add_u64 v[228:229], v[228:229], 0, v[182:183]
	v_cvt_pk_bf16_f32 v192, v192, v193
	v_cvt_pk_bf16_f32 v193, v194, v195
	v_pk_add_f32 v[224:225], v[48:49], v[132:133]
	global_store_dwordx2 v[228:229], v[192:193], off
	v_cvt_pk_bf16_f32 v192, v226, v227
	v_cvt_pk_bf16_f32 v193, v224, v225
	global_store_dwordx2 v[228:229], v[192:193], off offset:2048
	v_lshl_add_u64 v[192:193], s[78:79], 0, v[200:201]
	v_lshl_add_u64 v[192:193], v[192:193], 0, v[178:179]
	global_store_dwordx4 v[192:193], v[196:199], off
	v_lshl_add_u64 v[192:193], s[78:79], 0, v[202:203]
	v_lshl_add_u64 v[192:193], v[192:193], 0, v[178:179]
	global_store_dwordx4 v[192:193], v[158:161], off
	v_add_u32_e32 v192, 0xffff7f01, v191
	v_ashrrev_i32_e32 v193, 31, v192
	v_add_u32_e32 v158, 0xffff7f00, v191
	v_ashrrev_i32_e32 v159, 31, v158
	v_lshlrev_b64 v[196:197], 12, v[158:159]
	v_lshlrev_b64 v[198:199], 12, v[192:193]
	v_lshl_add_u64 v[158:159], s[74:75], 0, v[196:197]
	v_lshl_add_u64 v[192:193], s[74:75], 0, v[198:199]
	v_lshl_add_u64 v[158:159], v[158:159], 0, v[178:179]
	v_lshl_add_u64 v[192:193], v[192:193], 0, v[178:179]
	v_mad_i64_i32 v[224:225], s[12:13], v0, s33, v[180:181]
	v_lshl_add_u64 v[224:225], v[224:225], 0, v[182:183]
	v_add_u32_e32 v0, 0xa0, v190
	s_waitcnt vmcnt(8)
; __device__ __forceinline__ unsigned cvt_pk_bf16(float lo, float hi) { unsigned r; asm volatile("v_cvt_pk_bf16_f32 %0, %1, %2" : "=v"(r) : "v"(lo), "v"(hi)); return r; }
;     __device__ __forceinline__ void operator()(const f32x4 (&acc)[2][2][4][2], const Unit& u, int wr, int wc, int fr, int fq) const {
;     ...
;                 for (int m = 0; m < 4; ++m) { const int r = rbase + HALF + 16 * m, sb = r - MP;
;                     const f32x4 z2 = *(const f32x4*)(st + (size_t)(sb * 2) * D + xch), z1 = *(const f32x4*)(st + (size_t)(sb * 2 + 1) * D + xch);
;                     const f32x4 ua = acc[1][0][m][0] * (w0 * z2 + w1 * z1 + w2 * z[m]), ma = acc[1][1][m][1] + bm;
;                     bf16_t* rowp = O + (size_t)r * DP + xch;
;                     u32x2 a; a.x = cvt_pk_bf16(ua[0], ua[1]); a.y = cvt_pk_bf16(ua[2], ua[3]); *(u32x2*)(rowp + C_UA) = a;
;                     u32x2 g; g.x = cvt_pk_bf16(ma[0], ma[1]); g.y = cvt_pk_bf16(ma[2], ma[3]); *(u32x2*)(rowp + C_MA) = g;
;                     *(f32x4*)(outs + (size_t)(sb * 2) * D + xch) = z1; *(f32x4*)(outs + (size_t)(sb * 2 + 1) * D + xch) = z[m]; }
	v_mov_b64_e32 v[158:159], v[74:75]
	v_mov_b64_e32 v[160:161], v[76:77]
	v_mov_b64_e32 v[192:193], v[78:79]
	v_mov_b64_e32 v[194:195], v[80:81]
	v_pk_mul_f32 v[202:203], v[142:143], v[192:193]
	v_pk_mul_f32 v[200:201], v[144:145], v[194:195]
	v_pk_fma_f32 v[158:159], v[134:135], v[158:159], v[202:203]
	v_pk_fma_f32 v[160:161], v[136:137], v[160:161], v[200:201]
	v_pk_fma_f32 v[158:159], v[154:155], v[138:139], v[158:159]
	v_pk_fma_f32 v[160:161], v[156:157], v[140:141], v[160:161]
	v_pk_mul_f32 v[158:159], v[50:51], v[158:159]
	v_pk_mul_f32 v[160:161], v[52:53], v[160:161]
	v_cvt_pk_bf16_f32 v158, v158, v159
	v_pk_add_f32 v[200:201], v[32:33], v[132:133]
	v_cvt_pk_bf16_f32 v159, v160, v161
	v_pk_add_f32 v[202:203], v[30:31], v[130:131]
	global_store_dwordx2 v[224:225], v[158:159], off
	v_cvt_pk_bf16_f32 v158, v202, v203
	v_cvt_pk_bf16_f32 v159, v200, v201
	global_store_dwordx2 v[224:225], v[158:159], off offset:2048
	v_lshl_add_u64 v[158:159], s[78:79], 0, v[196:197]
	v_lshl_add_u64 v[158:159], v[158:159], 0, v[178:179]
	global_store_dwordx4 v[158:159], v[192:195], off
	v_lshl_add_u64 v[158:159], s[78:79], 0, v[198:199]
	v_lshl_add_u64 v[158:159], v[158:159], 0, v[178:179]
	global_store_dwordx4 v[158:159], v[154:157], off
	v_lshlrev_b32_e32 v158, 1, v0
	v_mad_i64_i32 v[200:201], s[12:13], v0, s33, v[180:181]
	v_add_u32_e32 v154, 0xffff7f00, v158
	v_add_u32_e32 v158, 0xffff7f01, v158
	v_ashrrev_i32_e32 v155, 31, v154
	v_ashrrev_i32_e32 v159, 31, v158
	v_lshlrev_b64 v[192:193], 12, v[154:155]
	v_lshlrev_b64 v[194:195], 12, v[158:159]
	v_lshl_add_u64 v[154:155], s[74:75], 0, v[192:193]
	v_lshl_add_u64 v[158:159], s[74:75], 0, v[194:195]
	v_lshl_add_u64 v[154:155], v[154:155], 0, v[178:179]
	v_lshl_add_u64 v[158:159], v[158:159], 0, v[178:179]
	v_lshl_add_u64 v[200:201], v[200:201], 0, v[182:183]
	v_add_u32_e32 v0, 0xb0, v190
	s_waitcnt vmcnt(10)
	v_mov_b64_e32 v[154:155], v[82:83]
	v_mov_b64_e32 v[156:157], v[84:85]
	v_mov_b64_e32 v[158:159], v[86:87]
	v_mov_b64_e32 v[160:161], v[88:89]
	v_pk_mul_f32 v[198:199], v[142:143], v[158:159]
	v_pk_mul_f32 v[196:197], v[144:145], v[160:161]
	v_pk_fma_f32 v[154:155], v[134:135], v[154:155], v[198:199]
	v_pk_fma_f32 v[156:157], v[136:137], v[156:157], v[196:197]
	v_pk_fma_f32 v[154:155], v[150:151], v[138:139], v[154:155]
	v_pk_fma_f32 v[156:157], v[152:153], v[140:141], v[156:157]
	v_pk_mul_f32 v[154:155], v[34:35], v[154:155]
	v_pk_mul_f32 v[156:157], v[36:37], v[156:157]
	v_cvt_pk_bf16_f32 v154, v154, v155
	v_pk_add_f32 v[196:197], v[16:17], v[132:133]
	v_cvt_pk_bf16_f32 v155, v156, v157
	v_pk_add_f32 v[198:199], v[14:15], v[130:131]
	global_store_dwordx2 v[200:201], v[154:155], off
	v_cvt_pk_bf16_f32 v154, v198, v199
	v_cvt_pk_bf16_f32 v155, v196, v197
	global_store_dwordx2 v[200:201], v[154:155], off offset:2048
	v_lshl_add_u64 v[154:155], s[78:79], 0, v[192:193]
	v_lshl_add_u64 v[154:155], v[154:155], 0, v[178:179]
	global_store_dwordx4 v[154:155], v[158:161], off
	v_lshl_add_u64 v[154:155], s[78:79], 0, v[194:195]
	v_lshl_add_u64 v[154:155], v[154:155], 0, v[178:179]
	global_store_dwordx4 v[154:155], v[150:153], off
	v_lshlrev_b32_e32 v154, 1, v0
	v_pk_add_f32 v[130:131], v[2:3], v[130:131]
	v_add_u32_e32 v150, 0xffff7f00, v154
	v_add_u32_e32 v154, 0xffff7f01, v154
	v_ashrrev_i32_e32 v151, 31, v150
	v_ashrrev_i32_e32 v155, 31, v154
	v_lshlrev_b64 v[158:159], 12, v[150:151]
	v_lshlrev_b64 v[160:161], 12, v[154:155]
	v_lshl_add_u64 v[150:151], s[74:75], 0, v[158:159]
	v_lshl_add_u64 v[154:155], s[74:75], 0, v[160:161]
	v_lshl_add_u64 v[150:151], v[150:151], 0, v[178:179]
	v_lshl_add_u64 v[154:155], v[154:155], 0, v[178:179]
	v_pk_add_f32 v[132:133], v[4:5], v[132:133]
	s_waitcnt vmcnt(12)
	v_mov_b64_e32 v[150:151], v[90:91]
	v_mov_b64_e32 v[152:153], v[92:93]
	v_mov_b64_e32 v[154:155], v[94:95]
	v_mov_b64_e32 v[156:157], v[96:97]
	v_pk_mul_f32 v[142:143], v[142:143], v[154:155]
	v_pk_mul_f32 v[144:145], v[144:145], v[156:157]
	v_pk_fma_f32 v[134:135], v[134:135], v[150:151], v[142:143]
	v_pk_fma_f32 v[136:137], v[136:137], v[152:153], v[144:145]
	v_pk_fma_f32 v[134:135], v[146:147], v[138:139], v[134:135]
	v_mad_i64_i32 v[138:139], s[12:13], v0, s33, v[180:181]
	v_pk_fma_f32 v[136:137], v[148:149], v[140:141], v[136:137]
	v_pk_mul_f32 v[134:135], v[18:19], v[134:135]
	v_lshl_add_u64 v[138:139], v[138:139], 0, v[182:183]
	v_pk_mul_f32 v[136:137], v[20:21], v[136:137]
	v_cvt_pk_bf16_f32 v134, v134, v135
	v_lshl_add_u64 v[180:181], s[78:79], 0, v[160:161]
	v_cvt_pk_bf16_f32 v135, v136, v137
	global_store_dwordx2 v[138:139], v[134:135], off
	v_cvt_pk_bf16_f32 v130, v130, v131
	v_cvt_pk_bf16_f32 v131, v132, v133
	global_store_dwordx2 v[138:139], v[130:131], off offset:2048
	v_lshl_add_u64 v[130:131], s[78:79], 0, v[158:159]
	v_lshl_add_u64 v[130:131], v[130:131], 0, v[178:179]
	global_store_dwordx4 v[130:131], v[154:157], off
